# group-barrier fast path: no s_sleep between polls; on top of v65
# speedup vs baseline: 1.0062x; 1.0028x over previous
; __device__ __forceinline__ unsigned xb_ld(unsigned* p)              { return __hip_atomic_load(p, __ATOMIC_RELAXED, __HIP_MEMORY_SCOPE_AGENT); }
; __device__ __forceinline__ unsigned xb_add(unsigned* p, unsigned v) { return __hip_atomic_fetch_add(p, v, __ATOMIC_RELAXED, __HIP_MEMORY_SCOPE_AGENT); }
; #define XB_SPIN(cond, bar) do { unsigned _sp = 0; while (cond) { __builtin_amdgcn_s_sleep(1); \
;     if ((++_sp & 255u) == 0u) { if (xb_ld(&(bar)[XB_TMO])) break; if (_sp > XB_SPIN_CAP) { atomicAdd(&(bar)[XB_TMO], 1u); break; } } } } while (0)
; __device__ __forceinline__ void xcd_barrier(const XcdBarrier& b) {
;     ...
;             else XB_SPIN(xb_ld(&bar[XB_TOPGEN]) == tg, bar);
;             __builtin_amdgcn_fence(__ATOMIC_ACQUIRE, "agent");
;             xb_add(&bar[XB_XGEN(b.x)], 1u);
;             asm volatile("s_waitcnt vmcnt(0)" ::: "memory");
;         } else {
;             XB_SPIN(xb_ld(&bar[XB_XGEN(b.x)]) == gen, bar);
.Lgb_spin_g1:
	global_load_dword v3, v0, s[38:39] sc1
	s_waitcnt vmcnt(0)
	v_sub_u32_e32 v3, v3, v2
	v_cmp_gt_i32_e32 vcc, 0, v3
	s_cbranch_vccz .Lgb_done_g1
	s_add_i32 s40, s40, 1
	s_cmp_lt_u32 s40, 0x100000
	s_cbranch_scc1 .Lgb_spin_g1
